# MoBA gate loop flattened: no per-block exec branching (unused past-block gates computed but ignored), 8 LDS reads batched per half
# baseline (speedup 1.0000x reference)
; #define LAS __attribute__((address_space(3)))
; __device__ __forceinline__ void moba_select(LAS unsigned char* lds, const bf16_t* Qp, int ld, int rowbase, int ob, const float* kmean_bh) {
;     ...
;       for (int c = 0; c < 16; ++c) {
;           const u32x4 qv = *(const u32x4*)(qrow + c * 8);
;           float qfv[8]; qfv[0] = bflo(qv.x); qfv[1] = bfhi(qv.x); qfv[2] = bflo(qv.y); qfv[3] = bfhi(qv.y); qfv[4] = bflo(qv.z); qfv[5] = bfhi(qv.z); qfv[6] = bflo(qv.w); qfv[7] = bfhi(qv.w);
; #pragma unroll
;           for (int jj = 0; jj < 8; ++jj) { const int j = 2 * jj + par;
;               if (j < ob) { const LAS float* km = km_s + j * 128 + c * 8; const f32x4 ka = *(const LAS f32x4*)km, kb = *(const LAS f32x4*)(km + 4);
;                   acc[jj] += qfv[0] * ka[0] + qfv[1] * ka[1] + qfv[2] * ka[2] + qfv[3] * ka[3] + qfv[4] * kb[0] + qfv[5] * kb[1] + qfv[6] * kb[2] + qfv[7] * kb[3]; } }
;       }
.LBB0_891:
	v_add_u32_e32 v0, s18, v182
	s_waitcnt vmcnt(0)
	v_lshlrev_b32_e32 v2, 16, v230
	v_and_b32_e32 v3, 0xffff0000, v230
	v_and_b32_e32 v5, 0xffff0000, v231
	v_lshlrev_b32_e32 v4, 16, v231
	v_and_b32_e32 v7, 0xffff0000, v232
	v_lshlrev_b32_e32 v6, 16, v232
	v_and_b32_e32 v35, 0xffff0000, v233
	v_lshlrev_b32_e32 v34, 16, v233
	v_lshl_add_u64 v[32:33], v[32:33], 0, 16
	global_load_dwordx4 v[230:233], v[32:33], off
	v_add_u32_e32 v36, 0x1b000, v0
	ds_read_b128 v[44:47], v36
	ds_read_b128 v[48:51], v36 offset:16
	ds_read_b128 v[52:55], v36 offset:1024
	ds_read_b128 v[56:59], v36 offset:1040
	ds_read_b128 v[60:63], v36 offset:2048
	ds_read_b128 v[64:67], v36 offset:2064
	ds_read_b128 v[68:71], v36 offset:3072
	ds_read_b128 v[72:75], v36 offset:3088
	s_waitcnt lgkmcnt(7)
	v_pk_mul_f32 v[44:45], v[44:45], v[2:3]
	v_pk_mul_f32 v[46:47], v[46:47], v[4:5]
	v_add_f32_e32 v37, v44, v45
	v_add_f32_e32 v37, v46, v37
	s_waitcnt lgkmcnt(6)
	v_pk_mul_f32 v[48:49], v[48:49], v[6:7]
	v_add_f32_e32 v37, v47, v37
	v_add_f32_e32 v37, v48, v37
	v_pk_mul_f32 v[50:51], v[50:51], v[34:35]
	v_add_f32_e32 v37, v49, v37
	v_add_f32_e32 v37, v50, v37
	v_add_f32_e32 v37, v51, v37
	v_add_f32_e32 v24, v24, v37
	s_waitcnt lgkmcnt(5)
	v_pk_mul_f32 v[52:53], v[52:53], v[2:3]
	v_pk_mul_f32 v[54:55], v[54:55], v[4:5]
	v_add_f32_e32 v37, v52, v53
	v_add_f32_e32 v37, v54, v37
	s_waitcnt lgkmcnt(4)
	v_pk_mul_f32 v[56:57], v[56:57], v[6:7]
	v_add_f32_e32 v37, v55, v37
	v_add_f32_e32 v37, v56, v37
	v_pk_mul_f32 v[58:59], v[58:59], v[34:35]
	v_add_f32_e32 v37, v57, v37
	v_add_f32_e32 v37, v58, v37
	v_add_f32_e32 v37, v59, v37
	v_add_f32_e32 v25, v25, v37
	s_waitcnt lgkmcnt(3)
	v_pk_mul_f32 v[60:61], v[60:61], v[2:3]
	v_pk_mul_f32 v[62:63], v[62:63], v[4:5]
	v_add_f32_e32 v37, v60, v61
	v_add_f32_e32 v37, v62, v37
	s_waitcnt lgkmcnt(2)
	v_pk_mul_f32 v[64:65], v[64:65], v[6:7]
	v_add_f32_e32 v37, v63, v37
	v_add_f32_e32 v37, v64, v37
	v_pk_mul_f32 v[66:67], v[66:67], v[34:35]
	v_add_f32_e32 v37, v65, v37
	v_add_f32_e32 v37, v66, v37
	v_add_f32_e32 v37, v67, v37
	v_add_f32_e32 v26, v26, v37
	s_waitcnt lgkmcnt(1)
	v_pk_mul_f32 v[68:69], v[68:69], v[2:3]
	v_pk_mul_f32 v[70:71], v[70:71], v[4:5]
	v_add_f32_e32 v37, v68, v69
	v_add_f32_e32 v37, v70, v37
	s_waitcnt lgkmcnt(0)
	v_pk_mul_f32 v[72:73], v[72:73], v[6:7]
	v_add_f32_e32 v37, v71, v37
	v_add_f32_e32 v37, v72, v37
	v_pk_mul_f32 v[74:75], v[74:75], v[34:35]
	v_add_f32_e32 v37, v73, v37
	v_add_f32_e32 v37, v74, v37
	v_add_f32_e32 v37, v75, v37
	v_add_f32_e32 v27, v27, v37
	ds_read_b128 v[44:47], v36 offset:4096
	ds_read_b128 v[48:51], v36 offset:4112
	ds_read_b128 v[52:55], v36 offset:5120
	ds_read_b128 v[56:59], v36 offset:5136
	ds_read_b128 v[60:63], v36 offset:6144
	ds_read_b128 v[64:67], v36 offset:6160
	ds_read_b128 v[68:71], v36 offset:7168
	ds_read_b128 v[72:75], v36 offset:7184
	s_waitcnt lgkmcnt(7)
	v_pk_mul_f32 v[44:45], v[44:45], v[2:3]
	v_pk_mul_f32 v[46:47], v[46:47], v[4:5]
	v_add_f32_e32 v37, v44, v45
	v_add_f32_e32 v37, v46, v37
	s_waitcnt lgkmcnt(6)
	v_pk_mul_f32 v[48:49], v[48:49], v[6:7]
	v_add_f32_e32 v37, v47, v37
	v_add_f32_e32 v37, v48, v37
	v_pk_mul_f32 v[50:51], v[50:51], v[34:35]
	v_add_f32_e32 v37, v49, v37
	v_add_f32_e32 v37, v50, v37
	v_add_f32_e32 v37, v51, v37
	v_add_f32_e32 v28, v28, v37
	s_waitcnt lgkmcnt(5)
	v_pk_mul_f32 v[52:53], v[52:53], v[2:3]
	v_pk_mul_f32 v[54:55], v[54:55], v[4:5]
	v_add_f32_e32 v37, v52, v53
	v_add_f32_e32 v37, v54, v37
	s_waitcnt lgkmcnt(4)
	v_pk_mul_f32 v[56:57], v[56:57], v[6:7]
	v_add_f32_e32 v37, v55, v37
	v_add_f32_e32 v37, v56, v37
	v_pk_mul_f32 v[58:59], v[58:59], v[34:35]
	v_add_f32_e32 v37, v57, v37
	v_add_f32_e32 v37, v58, v37
	v_add_f32_e32 v37, v59, v37
	v_add_f32_e32 v29, v29, v37
	s_waitcnt lgkmcnt(3)
	v_pk_mul_f32 v[60:61], v[60:61], v[2:3]
	v_pk_mul_f32 v[62:63], v[62:63], v[4:5]
	v_add_f32_e32 v37, v60, v61
	v_add_f32_e32 v37, v62, v37
	s_waitcnt lgkmcnt(2)
	v_pk_mul_f32 v[64:65], v[64:65], v[6:7]
	v_add_f32_e32 v37, v63, v37
	v_add_f32_e32 v37, v64, v37
	v_pk_mul_f32 v[66:67], v[66:67], v[34:35]
	v_add_f32_e32 v37, v65, v37
	v_add_f32_e32 v37, v66, v37
	v_add_f32_e32 v37, v67, v37
	v_add_f32_e32 v30, v30, v37
	s_waitcnt lgkmcnt(1)
	v_pk_mul_f32 v[68:69], v[68:69], v[2:3]
	v_pk_mul_f32 v[70:71], v[70:71], v[4:5]
	v_add_f32_e32 v37, v68, v69
	v_add_f32_e32 v37, v70, v37
	s_waitcnt lgkmcnt(0)
	v_pk_mul_f32 v[72:73], v[72:73], v[6:7]
	v_add_f32_e32 v37, v71, v37
	v_add_f32_e32 v37, v72, v37
	v_pk_mul_f32 v[74:75], v[74:75], v[34:35]
	v_add_f32_e32 v37, v73, v37
	v_add_f32_e32 v37, v74, v37
	v_add_f32_e32 v37, v75, v37
	v_add_f32_e32 v31, v31, v37
	s_add_i32 s18, s18, 32
	s_cmpk_eq_i32 s18, 0x200
	s_cbranch_scc0 .LBB0_891
